# indexer histogram zeroing: two 16-byte LDS stores per thread replace the 8-trip exec-masked 4-byte store loop (unit start and radix passes)
# speedup vs baseline: 1.0096x; 1.0018x over previous
; #define LAS __attribute__((address_space(3)))
; __device__ __forceinline__ void sel_unit(LAS char* lds, int b, int u, const bf16_t* QI, const bf16_t* KIDX, const float* WIDX, unsigned long long* MASK) {
;     ...
; #pragma unroll
;     for (int i = 0; i < 2; ++i) { const int id = tid + 512 * i, row = id >> 6, ch = id & 63;
;         *(LAS u32x4*)(lds + L_QI + row * 1024 + ((ch ^ (row & 15)) << 4)) = *(const u32x4*)(QI + (rowbase + q0 + row) * 512 + ch * 8); }
;     for (int i = tid; i < 4096; i += 512) hist[i] = 0u;
;     if (tid < 16) { pref[tid] = 0u; kremS[tid] = 256u; }
.LBB0_648:
	s_getreg_b32 s2, hwreg(HW_REG_HW_ID, 0, 6)
	s_lshl_b32 s2, s2, 2
	s_and_b32 s2, s2, 0xfc
	s_add_i32 s2, s2, 0x20040
	v_mov_b32_e32 v0, s2
	ds_read_b32 v0, v0
	s_ashr_i32 s1, s0, 31
	s_lshr_b32 s1, s1, 30
	s_add_i32 s2, s0, s1
	s_and_b32 s1, s2, -4
	s_sub_i32 s0, s0, s1
	s_waitcnt lgkmcnt(0)
	v_readfirstlane_b32 s1, v0
	v_mov_b32_e32 v0, v1
	s_lshl_b32 s2, s2, 2
	v_mbcnt_lo_u32_b32 v0, -1, v0
	v_mbcnt_hi_u32_b32 v2, -1, v0
	s_and_b32 s2, s2, -16
	v_lshl_or_b32 v58, s1, 6, v2
	s_ashr_i32 s1, s0, 31
	s_sub_i32 s2, 0xff0, s2
	s_lshl_b64 s[0:1], s[0:1], 12
	s_lshr_b32 s34, s2, 6
	s_add_u32 s52, s0, s2
	s_addc_u32 s53, s1, 0
	v_and_b32_e32 v59, 15, v2
	v_readfirstlane_b32 s47, v58
	s_cmpk_lt_u32 s2, 0x100
	s_mov_b64 s[2:3], -1
	s_cbranch_scc1 .LBB0_1103
	v_ashrrev_i32_e32 v10, 6, v58
	v_and_b32_e32 v3, 63, v2
	v_ashrrev_i32_e32 v11, 31, v10
	v_lshlrev_b32_e32 v0, 4, v3
	v_lshl_add_u64 v[4:5], s[52:53], 0, v[10:11]
	v_lshl_add_u64 v[8:9], s[70:71], 0, v[0:1]
	v_lshlrev_b64 v[4:5], 10, v[4:5]
	v_lshl_add_u64 v[4:5], v[8:9], 0, v[4:5]
	global_load_dwordx4 v[4:7], v[4:5], off
	v_lshlrev_b32_e32 v0, 10, v10
	v_bitop3_b32 v10, v10, v3, 15 bitop3:0x6c
	v_lshlrev_b32_e32 v10, 4, v10
	v_add3_u32 v0, 0, v0, v10
	v_cmp_gt_i32_e32 vcc, s96, v58
	s_waitcnt vmcnt(0)
	ds_write_b128 v0, v[4:7]
	v_add_u32_e32 v0, 0x200, v58
	v_ashrrev_i32_e32 v10, 6, v0
	v_ashrrev_i32_e32 v11, 31, v10
	v_lshl_add_u64 v[4:5], s[52:53], 0, v[10:11]
	v_lshlrev_b64 v[4:5], 10, v[4:5]
	v_lshl_add_u64 v[4:5], v[8:9], 0, v[4:5]
	global_load_dwordx4 v[4:7], v[4:5], off
	v_bitop3_b32 v3, v10, v3, 15 bitop3:0x6c
	v_lshlrev_b32_e32 v0, 10, v10
	v_lshlrev_b32_e32 v3, 4, v3
	v_add3_u32 v0, 0, v0, v3
	s_waitcnt vmcnt(0)
	ds_write_b128 v0, v[4:7]
	s_and_saveexec_b64 s[2:3], vcc
	s_cbranch_execz .LBB0_652
	v_lshlrev_b32_e32 v0, 5, v58
	v_mov_b64_e32 v[36:37], 0
	v_mov_b64_e32 v[38:39], 0
	ds_write_b128 v0, v[36:39] offset:16384
	ds_write_b128 v0, v[36:39] offset:16400

; __device__ __forceinline__ void sel_unit(LAS char* lds, int b, int u, const bf16_t* QI, const bf16_t* KIDX, const float* WIDX, unsigned long long* MASK) {
;     ...
;         { const int t_ = opaque_tid(); for (int i = t_; i < 4096; i += 512) hist[i] = 0u; }
.LBB0_706:
	s_getreg_b32 s2, hwreg(HW_REG_HW_ID, 0, 6)
	s_lshl_b32 s2, s2, 2
	s_and_b32 s2, s2, 0xfc
	s_add_i32 s2, s2, 0x20040
	v_mov_b32_e32 v2, s2
	ds_read_b32 v2, v2
	s_waitcnt lgkmcnt(0)
	v_readfirstlane_b32 s2, v2
	v_mov_b32_e32 v2, 0
	s_nop 0
	v_mbcnt_lo_u32_b32 v2, -1, v2
	v_mbcnt_hi_u32_b32 v2, -1, v2
	v_lshl_or_b32 v3, s2, 6, v2
	v_cmp_gt_i32_e32 vcc, s96, v3
	s_and_saveexec_b64 s[2:3], vcc
	s_cbranch_execz .LBB0_709
	v_lshlrev_b32_e32 v2, 5, v3
	v_mov_b64_e32 v[36:37], 0
	v_mov_b64_e32 v[38:39], 0
	ds_write_b128 v2, v[36:39] offset:16384
	ds_write_b128 v2, v[36:39] offset:16400
